# context-row LayerNorm phases moved to workgroups 192-255, no grid barrier after them; counter release/acquire before the next GEMM's first epilogue
# speedup vs baseline: 1.1403x; 1.0001x over previous
_Z10hybrid_fwd4Args:
	s_mov_b32 s3, 0
	v_writelane_b32 v255, s3, 62
	s_load_dwordx4 s[52:55], s[0:1], 0x90
	s_mov_b32 s78, s2
	s_add_u32 s2, s0, 0xa0
	v_writelane_b32 v252, s0, 0
	s_addc_u32 s3, s1, 0
	v_and_b32_e32 v191, 0x3ff, v0
	v_writelane_b32 v252, s1, 1
	v_writelane_b32 v252, s2, 2
	v_cmp_gt_u32_e32 vcc, 64, v191
	s_nop 0
	v_writelane_b32 v252, s3, 3
	s_and_saveexec_b64 s[0:1], vcc
	v_lshl_add_u32 v1, v191, 2, 0
	v_add_u32_e32 v1, 0x24000, v1
	v_mov_b32_e32 v2, 0
	ds_write_b32 v1, v2
	s_or_b64 exec, exec, s[0:1]
	v_readlane_b32 s0, v252, 0
	v_readlane_b32 s1, v252, 1
	s_load_dwordx2 s[80:81], s[0:1], 0xa0
	s_waitcnt lgkmcnt(0)
	s_barrier
	s_getreg_b32 s0, hwreg(HW_REG_XCC_ID, 0, 4)
	s_and_b32 s4, s0, 15
	v_cmp_eq_u32_e64 s[2:3], 0, v191
	s_mov_b64 s[0:1], exec
	s_nop 0
	v_writelane_b32 v252, s2, 4
	s_nop 1
	v_writelane_b32 v252, s3, 5
	s_and_b64 s[2:3], s[0:1], s[2:3]
	s_mov_b64 exec, s[2:3]
	s_cbranch_execz .LBB0_5
	s_mov_b64 s[2:3], exec
	v_mbcnt_lo_u32_b32 v1, s2, 0
	v_mbcnt_hi_u32_b32 v1, s3, v1
	v_cmp_eq_u32_e32 vcc, 0, v1
	s_and_b64 s[6:7], exec, vcc
	s_mov_b64 exec, s[6:7]
	s_cbranch_execz .LBB0_5
	s_lshl_b32 s5, s4, 8
	s_bcnt1_i32_b64 s2, s[2:3]
	v_mov_b32_e32 v1, s5
	v_mov_b32_e32 v2, s2
	global_atomic_add v1, v2, s[52:53] offset:1024

.LBB0_48:
	v_readlane_b32 s10, v254, 33
	v_readlane_b32 s11, v254, 34
	s_and_b64 s[10:11], s[10:11], exec
	s_movk_i32 s9, 0x4200
	s_cselect_b32 s25, s9, 0x4000
	v_readlane_b32 s9, v253, 43
	v_readlane_b32 s10, v254, 0
	s_add_i32 s12, s10, s9
	s_addk_i32 s12, 0xfa00
	s_cmp_lt_i32 s12, s9
	s_cbranch_scc1 .LBB0_66
	s_cmp_ge_i32 s12, s25
	v_readlane_b32 s11, v254, 1
	s_cbranch_scc1 .LBB0_66
	s_xor_b64 s[10:11], s[6:7], -1
	v_cndmask_b32_e64 v0, 0, 1, s[10:11]
	v_xor_b32_e32 v2, 1, v214
	v_readfirstlane_b32 s10, v0
	v_and_b32_e32 v0, 64, v214
	v_add_u32_e32 v0, 64, v0
	v_cmp_lt_i32_e32 vcc, v2, v0
	s_load_dwordx4 s[16:19], s[42:43], 0x78
	s_lshl_b32 s9, s88, 1
	v_cndmask_b32_e32 v2, v214, v2, vcc
	v_lshlrev_b32_e32 v23, 2, v2
	v_xor_b32_e32 v2, 2, v214
	v_cmp_lt_i32_e32 vcc, v2, v0
	s_or_b32 s10, s9, s10
	s_ashr_i32 s11, s10, 31
	v_cndmask_b32_e32 v2, v214, v2, vcc
	v_lshlrev_b32_e32 v46, 2, v2
	v_xor_b32_e32 v2, 4, v214
	v_cmp_lt_i32_e32 vcc, v2, v0
	s_lshl_b64 s[10:11], s[10:11], 12
	s_waitcnt lgkmcnt(0)
	s_add_u32 s20, s16, s10
	v_cndmask_b32_e32 v2, v214, v2, vcc
	v_lshlrev_b32_e32 v47, 2, v2
	v_xor_b32_e32 v2, 8, v214
	v_cmp_lt_i32_e32 vcc, v2, v0
	s_addc_u32 s21, s17, s11
	v_readlane_b32 s14, v254, 33
	v_cndmask_b32_e32 v2, v214, v2, vcc
	v_lshlrev_b32_e32 v48, 2, v2
	v_xor_b32_e32 v2, 16, v214
	v_cmp_lt_i32_e32 vcc, v2, v0
	s_add_u32 s10, s18, s10
	v_readlane_b32 s15, v254, 34
	v_cndmask_b32_e32 v2, v214, v2, vcc
	v_lshlrev_b32_e32 v49, 2, v2
	v_xor_b32_e32 v2, 32, v214
	s_addc_u32 s11, s19, s11
	s_nor_b64 s[14:15], s[14:15], s[6:7]
	s_lshl_b32 s8, s8, 2
	v_cmp_lt_i32_e32 vcc, v2, v0
	s_add_u32 s8, s22, s8
	s_addc_u32 s9, s23, 0
	v_cndmask_b32_e32 v0, v214, v2, vcc
	s_add_i32 s13, s54, 4
	v_lshlrev_b32_e32 v50, 2, v0
	v_lshlrev_b32_e32 v0, 4, v223
	s_cmp_lt_u32 s13, 13
	v_lshl_add_u64 v[2:3], s[8:9], 0, v[0:1]
	v_lshl_add_u64 v[28:29], s[10:11], 0, v[0:1]
	s_load_dwordx4 s[8:11], s[42:43], 0x88
	s_cselect_b64 s[16:17], -1, 0
	s_and_b64 s[6:7], s[6:7], s[16:17]
	v_readlane_b32 s16, v252, 12
	v_readlane_b32 s17, v252, 13
	s_and_b64 s[16:17], s[6:7], s[16:17]
	s_mov_b64 s[6:7], 0xc000
	v_lshlrev_b32_e32 v22, 2, v223
	v_lshl_add_u64 v[24:25], v[2:3], 0, s[6:7]
	s_waitcnt lgkmcnt(0)
	v_lshl_add_u64 v[8:9], s[10:11], 0, v[0:1]
	s_mov_b64 s[6:7], 0xb100000
	v_or_b32_e32 v2, 0x100, v22
	v_or_b32_e32 v4, 0x200, v22
	v_or_b32_e32 v6, 0x300, v22
	v_lshl_add_u64 v[30:31], v[8:9], 0, s[6:7]
	v_readlane_b32 s6, v253, 44
	v_readlane_b32 s7, v254, 14
	v_lshl_add_u64 v[26:27], s[20:21], 0, v[0:1]
	s_add_i32 s18, s6, s7
	s_addk_i32 s18, 0xfa00
	v_lshlrev_b32_e32 v51, 2, v2
	v_lshlrev_b32_e32 v52, 2, v4
	v_lshlrev_b32_e32 v53, 2, v6
	s_branch .LBB0_51

.LBB0_66:
	s_cmpk_lt_i32 s78, 0xc0
	s_cbranch_scc1 .Lctxln_nopub
	s_waitcnt vmcnt(0)
	s_barrier
	v_readfirstlane_b32 s4, v191
	s_nop 3
	s_cmp_lg_u32 s4, 0
	s_cbranch_scc1 .Lctxln_nopub
	v_readlane_b32 s4, v254, 10
	v_readlane_b32 s5, v254, 11
	s_nop 3
	s_add_u32 s4, s4, 0x16800
	s_addc_u32 s5, s5, 0
	s_cmp_eq_u32 s54, 8
	s_cselect_b32 vcc_lo, 0x100, 0
	s_add_u32 s4, s4, vcc_lo
	s_addc_u32 s5, s5, 0
	s_mov_b64 vcc, exec
	s_mov_b64 exec, 1
	buffer_wbl2 sc1
	s_waitcnt vmcnt(0)
	global_atomic_add v1, v220, s[4:5]
	s_mov_b64 exec, vcc

.LBB0_923:
	v_writelane_b32 v255, s0, 40
	v_writelane_b32 v255, s1, 41
	v_writelane_b32 v255, s2, 42
	v_writelane_b32 v255, s3, 43
	v_writelane_b32 v255, s4, 44
	v_readlane_b32 s2, v254, 44
	v_readlane_b32 s3, v255, 62
	s_nop 3
	s_cmp_eq_u32 s2, s3
	s_cbranch_scc1 .Lacq_done_f
	s_cmp_eq_u32 s2, 6
	s_cbranch_scc0 .Lacq_done_f
	v_readlane_b32 s0, v254, 10
	v_readlane_b32 s1, v254, 11
	s_nop 3
	s_add_u32 s0, s0, 0x16800
	s_addc_u32 s1, s1, 0
	s_mov_b32 s3, 0
.Lacq_spin_f:
	global_load_dword v204, v1, s[0:1] sc1
	s_waitcnt vmcnt(0)
	v_readfirstlane_b32 s4, v204
	s_nop 3
	s_cmp_ge_u32 s4, 64
	s_cbranch_scc1 .Lacq_got_f
	s_sleep 2
	s_add_u32 s3, s3, 1
	s_cmp_lt_u32 s3, 0x4000
	s_cbranch_scc1 .Lacq_spin_f
.Lacq_got_f:
	buffer_inv sc1
	s_waitcnt vmcnt(0)
	v_writelane_b32 v255, s2, 62
.Lacq_done_f:
	v_readlane_b32 s0, v255, 40
	v_readlane_b32 s1, v255, 41
	v_readlane_b32 s2, v255, 42
	v_readlane_b32 s3, v255, 43
	v_readlane_b32 s4, v255, 44
	s_nop 3
	v_mul_f32_e32 v146, 0xbfb8aa3b, v126
	v_mul_f32_e32 v147, 0xbfb8aa3b, v127
	v_exp_f32_e32 v146, v146
	v_exp_f32_e32 v147, v147
	v_readlane_b32 s4, v254, 35
	v_lshl_add_u32 v143, s0, 8, v140
	v_add_f32_e32 v146, 1.0, v146
	v_add_f32_e32 v147, 1.0, v147
	v_rcp_f32_e32 v146, v146
	v_rcp_f32_e32 v147, v147
	s_lshl_b32 s0, s1, 7
	v_readlane_b32 s5, v254, 36
	s_ashr_i32 s1, s0, 31
	v_pk_mul_f32 v[126:127], v[126:127], v[146:147]
	v_mov_b64_e32 v[138:139], s[4:5]
	v_pk_mul_f32 v[122:123], v[122:123], v[126:127]
	v_mul_f32_e32 v126, 0xbfb8aa3b, v128
	v_mul_f32_e32 v127, 0xbfb8aa3b, v129
	v_exp_f32_e32 v126, v126
	v_exp_f32_e32 v127, v127
	s_movk_i32 s6, 0x1600
	v_mad_i64_i32 v[144:145], s[4:5], v143, s6, v[138:139]
	v_add_f32_e32 v126, 1.0, v126
	v_add_f32_e32 v127, 1.0, v127
	v_rcp_f32_e32 v126, v126
	v_rcp_f32_e32 v127, v127
	s_lshl_b64 s[0:1], s[0:1], 1
	v_readlane_b32 s8, v253, 49
	v_lshl_add_u64 v[144:145], v[144:145], 0, s[0:1]
	v_readlane_b32 s9, v253, 50
	v_pk_mul_f32 v[126:127], v[128:129], v[126:127]
	v_cvt_pk_bf16_f32 v122, v122, v123
	v_lshl_add_u64 v[144:145], v[144:145], 0, s[8:9]
	v_pk_mul_f32 v[124:125], v[124:125], v[126:127]
	v_lshl_add_u64 v[144:145], v[144:145], 0, v[0:1]
	v_cvt_pk_bf16_f32 v123, v124, v125
	global_store_dwordx2 v[144:145], v[122:123], off
	v_mul_f32_e32 v122, 0xbfb8aa3b, v118
	v_mul_f32_e32 v123, 0xbfb8aa3b, v119
	v_exp_f32_e32 v122, v122
	v_exp_f32_e32 v123, v123
	s_andn2_b64 vcc, exec, s[40:41]
	s_mov_b32 s39, 0xe7000
	v_add_f32_e32 v122, 1.0, v122
	v_add_f32_e32 v123, 1.0, v123
	v_rcp_f32_e32 v122, v122
	v_rcp_f32_e32 v123, v123
	s_mov_b64 s[48:49], 0xca00100
	v_pk_mul_f32 v[118:119], v[118:119], v[122:123]
	s_nop 0
	v_pk_mul_f32 v[114:115], v[114:115], v[118:119]
	v_mul_f32_e32 v118, 0xbfb8aa3b, v120
	v_mul_f32_e32 v119, 0xbfb8aa3b, v121
	v_exp_f32_e32 v118, v118
	v_exp_f32_e32 v119, v119
	v_cvt_pk_bf16_f32 v114, v114, v115
	v_add_f32_e32 v118, 1.0, v118
	v_add_f32_e32 v119, 1.0, v119
	v_rcp_f32_e32 v118, v118
	v_rcp_f32_e32 v119, v119
	s_nop 0
	v_pk_mul_f32 v[118:119], v[120:121], v[118:119]
	s_nop 0
	v_pk_mul_f32 v[116:117], v[116:117], v[118:119]
	s_nop 0
	v_cvt_pk_bf16_f32 v115, v116, v117
	v_mul_f32_e32 v116, 0xbfb8aa3b, v110
	v_mul_f32_e32 v117, 0xbfb8aa3b, v111
	v_exp_f32_e32 v116, v116
	v_exp_f32_e32 v117, v117
	global_store_dwordx2 v[144:145], v[114:115], off offset:32
	v_or_b32_e32 v114, 16, v143
	v_add_f32_e32 v116, 1.0, v116
	v_add_f32_e32 v117, 1.0, v117
	v_rcp_f32_e32 v116, v116
	v_rcp_f32_e32 v117, v117
	v_mad_i64_i32 v[114:115], s[4:5], v114, s6, v[138:139]
	v_lshl_add_u64 v[114:115], v[114:115], 0, s[0:1]
	v_pk_mul_f32 v[110:111], v[110:111], v[116:117]
	v_lshl_add_u64 v[114:115], v[114:115], 0, s[8:9]
	v_pk_mul_f32 v[106:107], v[106:107], v[110:111]
	v_mul_f32_e32 v110, 0xbfb8aa3b, v112
	v_mul_f32_e32 v111, 0xbfb8aa3b, v113
	v_exp_f32_e32 v110, v110
	v_exp_f32_e32 v111, v111
	v_lshl_add_u64 v[114:115], v[114:115], 0, v[0:1]
	v_cvt_pk_bf16_f32 v106, v106, v107
	v_add_f32_e32 v110, 1.0, v110
	v_add_f32_e32 v111, 1.0, v111
	v_rcp_f32_e32 v110, v110
	v_rcp_f32_e32 v111, v111
	s_nop 0
	v_pk_mul_f32 v[110:111], v[112:113], v[110:111]
	s_nop 0
	v_pk_mul_f32 v[108:109], v[108:109], v[110:111]
	s_nop 0
	v_cvt_pk_bf16_f32 v107, v108, v109
	global_store_dwordx2 v[114:115], v[106:107], off
	v_mul_f32_e32 v106, 0xbfb8aa3b, v102
	v_mul_f32_e32 v107, 0xbfb8aa3b, v103
	v_exp_f32_e32 v106, v106
	v_exp_f32_e32 v107, v107
	v_add_f32_e32 v106, 1.0, v106
	v_add_f32_e32 v107, 1.0, v107
	v_rcp_f32_e32 v106, v106
	v_rcp_f32_e32 v107, v107
	s_nop 0
	v_pk_mul_f32 v[102:103], v[102:103], v[106:107]
	s_nop 0
	v_pk_mul_f32 v[98:99], v[98:99], v[102:103]
	v_mul_f32_e32 v102, 0xbfb8aa3b, v104
	v_mul_f32_e32 v103, 0xbfb8aa3b, v105
	v_exp_f32_e32 v102, v102
	v_exp_f32_e32 v103, v103
	v_cvt_pk_bf16_f32 v98, v98, v99
	v_add_f32_e32 v102, 1.0, v102
	v_add_f32_e32 v103, 1.0, v103
	v_rcp_f32_e32 v102, v102
	v_rcp_f32_e32 v103, v103
	s_nop 0
	v_pk_mul_f32 v[102:103], v[104:105], v[102:103]
	s_nop 0
	v_pk_mul_f32 v[100:101], v[100:101], v[102:103]
	s_nop 0
	v_cvt_pk_bf16_f32 v99, v100, v101
	v_mul_f32_e32 v100, 0xbfb8aa3b, v94
	v_mul_f32_e32 v101, 0xbfb8aa3b, v95
	v_exp_f32_e32 v100, v100
	v_exp_f32_e32 v101, v101
	global_store_dwordx2 v[114:115], v[98:99], off offset:32
	v_or_b32_e32 v98, 32, v143
	v_add_f32_e32 v100, 1.0, v100
	v_add_f32_e32 v101, 1.0, v101
	v_rcp_f32_e32 v100, v100
	v_rcp_f32_e32 v101, v101
	v_mad_i64_i32 v[98:99], s[4:5], v98, s6, v[138:139]
	v_lshl_add_u64 v[98:99], v[98:99], 0, s[0:1]
	v_pk_mul_f32 v[94:95], v[94:95], v[100:101]
	v_lshl_add_u64 v[98:99], v[98:99], 0, s[8:9]
	v_pk_mul_f32 v[90:91], v[90:91], v[94:95]
	v_mul_f32_e32 v94, 0xbfb8aa3b, v96
	v_mul_f32_e32 v95, 0xbfb8aa3b, v97
	v_exp_f32_e32 v94, v94
	v_exp_f32_e32 v95, v95
	v_lshl_add_u64 v[98:99], v[98:99], 0, v[0:1]
	v_cvt_pk_bf16_f32 v90, v90, v91
	v_add_f32_e32 v94, 1.0, v94
	v_add_f32_e32 v95, 1.0, v95
	v_rcp_f32_e32 v94, v94
	v_rcp_f32_e32 v95, v95
	s_nop 0
	v_pk_mul_f32 v[94:95], v[96:97], v[94:95]
	s_nop 0
	v_pk_mul_f32 v[92:93], v[92:93], v[94:95]
	s_nop 0
	v_cvt_pk_bf16_f32 v91, v92, v93
	global_store_dwordx2 v[98:99], v[90:91], off
	v_mul_f32_e32 v90, 0xbfb8aa3b, v86
	v_mul_f32_e32 v91, 0xbfb8aa3b, v87
	v_exp_f32_e32 v90, v90
	v_exp_f32_e32 v91, v91
	v_add_f32_e32 v90, 1.0, v90
	v_add_f32_e32 v91, 1.0, v91
	v_rcp_f32_e32 v90, v90
	v_rcp_f32_e32 v91, v91
	s_nop 0
	v_pk_mul_f32 v[86:87], v[86:87], v[90:91]
	s_nop 0
	v_pk_mul_f32 v[82:83], v[82:83], v[86:87]
	v_mul_f32_e32 v86, 0xbfb8aa3b, v88
	v_mul_f32_e32 v87, 0xbfb8aa3b, v89
	v_exp_f32_e32 v86, v86
	v_exp_f32_e32 v87, v87
	v_cvt_pk_bf16_f32 v82, v82, v83
	v_add_f32_e32 v86, 1.0, v86
	v_add_f32_e32 v87, 1.0, v87
	v_rcp_f32_e32 v86, v86
	v_rcp_f32_e32 v87, v87
	s_nop 0
	v_pk_mul_f32 v[86:87], v[88:89], v[86:87]
	s_nop 0
	v_pk_mul_f32 v[84:85], v[84:85], v[86:87]
	s_nop 0
	v_cvt_pk_bf16_f32 v83, v84, v85
	v_mul_f32_e32 v84, 0xbfb8aa3b, v78
	v_mul_f32_e32 v85, 0xbfb8aa3b, v79
	v_exp_f32_e32 v84, v84
	v_exp_f32_e32 v85, v85
	global_store_dwordx2 v[98:99], v[82:83], off offset:32
	v_or_b32_e32 v82, 48, v143
	v_add_f32_e32 v84, 1.0, v84
	v_add_f32_e32 v85, 1.0, v85
	v_rcp_f32_e32 v84, v84
	v_rcp_f32_e32 v85, v85
	v_mad_i64_i32 v[82:83], s[4:5], v82, s6, v[138:139]
	v_lshl_add_u64 v[82:83], v[82:83], 0, s[0:1]
	v_pk_mul_f32 v[78:79], v[78:79], v[84:85]
	v_lshl_add_u64 v[82:83], v[82:83], 0, s[8:9]
	v_pk_mul_f32 v[74:75], v[74:75], v[78:79]
	v_mul_f32_e32 v78, 0xbfb8aa3b, v80
	v_mul_f32_e32 v79, 0xbfb8aa3b, v81
	v_exp_f32_e32 v78, v78
	v_exp_f32_e32 v79, v79
	v_lshl_add_u64 v[82:83], v[82:83], 0, v[0:1]
	v_cvt_pk_bf16_f32 v74, v74, v75
	v_add_f32_e32 v78, 1.0, v78
	v_add_f32_e32 v79, 1.0, v79
	v_rcp_f32_e32 v78, v78
	v_rcp_f32_e32 v79, v79
	s_nop 0
	v_pk_mul_f32 v[78:79], v[80:81], v[78:79]
	s_nop 0
	v_pk_mul_f32 v[76:77], v[76:77], v[78:79]
	s_nop 0
	v_cvt_pk_bf16_f32 v75, v76, v77
	global_store_dwordx2 v[82:83], v[74:75], off
	v_mul_f32_e32 v74, 0xbfb8aa3b, v70
	v_mul_f32_e32 v75, 0xbfb8aa3b, v71
	v_exp_f32_e32 v74, v74
	v_exp_f32_e32 v75, v75
	v_add_f32_e32 v74, 1.0, v74
	v_add_f32_e32 v75, 1.0, v75
	v_rcp_f32_e32 v74, v74
	v_rcp_f32_e32 v75, v75
	s_nop 0
	v_pk_mul_f32 v[70:71], v[70:71], v[74:75]
	s_nop 0
	v_pk_mul_f32 v[66:67], v[66:67], v[70:71]
	v_mul_f32_e32 v70, 0xbfb8aa3b, v72
	v_mul_f32_e32 v71, 0xbfb8aa3b, v73
	v_exp_f32_e32 v70, v70
	v_exp_f32_e32 v71, v71
	v_cvt_pk_bf16_f32 v66, v66, v67
	v_add_f32_e32 v70, 1.0, v70
	v_add_f32_e32 v71, 1.0, v71
	v_rcp_f32_e32 v70, v70
	v_rcp_f32_e32 v71, v71
	s_nop 0
	v_pk_mul_f32 v[70:71], v[72:73], v[70:71]
	s_nop 0
	v_pk_mul_f32 v[68:69], v[68:69], v[70:71]
	s_nop 0
	v_cvt_pk_bf16_f32 v67, v68, v69
	v_mul_f32_e32 v68, 0xbfb8aa3b, v62
	v_mul_f32_e32 v69, 0xbfb8aa3b, v63
	v_exp_f32_e32 v68, v68
	v_exp_f32_e32 v69, v69
	global_store_dwordx2 v[82:83], v[66:67], off offset:32
	v_add_u32_e32 v66, 0x80, v143
	v_add_f32_e32 v68, 1.0, v68
	v_add_f32_e32 v69, 1.0, v69
	v_rcp_f32_e32 v68, v68
	v_rcp_f32_e32 v69, v69
	v_mad_i64_i32 v[66:67], s[4:5], v66, s6, v[138:139]
	v_lshl_add_u64 v[66:67], v[66:67], 0, s[0:1]
	v_pk_mul_f32 v[62:63], v[62:63], v[68:69]
	v_lshl_add_u64 v[66:67], v[66:67], 0, s[8:9]
	v_pk_mul_f32 v[58:59], v[58:59], v[62:63]
	v_mul_f32_e32 v62, 0xbfb8aa3b, v64
	v_mul_f32_e32 v63, 0xbfb8aa3b, v65
	v_exp_f32_e32 v62, v62
	v_exp_f32_e32 v63, v63
	v_lshl_add_u64 v[66:67], v[66:67], 0, v[0:1]
	v_cvt_pk_bf16_f32 v58, v58, v59
	v_add_f32_e32 v62, 1.0, v62
	v_add_f32_e32 v63, 1.0, v63
	v_rcp_f32_e32 v62, v62
	v_rcp_f32_e32 v63, v63
	s_nop 0
	v_pk_mul_f32 v[62:63], v[64:65], v[62:63]
	s_nop 0
	v_pk_mul_f32 v[60:61], v[60:61], v[62:63]
	s_nop 0
	v_cvt_pk_bf16_f32 v59, v60, v61
	global_store_dwordx2 v[66:67], v[58:59], off
	v_mul_f32_e32 v58, 0xbfb8aa3b, v54
	v_mul_f32_e32 v59, 0xbfb8aa3b, v55
	v_exp_f32_e32 v58, v58
	v_exp_f32_e32 v59, v59
	v_add_f32_e32 v58, 1.0, v58
	v_add_f32_e32 v59, 1.0, v59
	v_rcp_f32_e32 v58, v58
	v_rcp_f32_e32 v59, v59
	s_nop 0
	v_pk_mul_f32 v[54:55], v[54:55], v[58:59]
	s_nop 0
	v_pk_mul_f32 v[50:51], v[50:51], v[54:55]
	v_mul_f32_e32 v54, 0xbfb8aa3b, v56
	v_mul_f32_e32 v55, 0xbfb8aa3b, v57
	v_exp_f32_e32 v54, v54
	v_exp_f32_e32 v55, v55
	v_cvt_pk_bf16_f32 v50, v50, v51
	v_add_f32_e32 v54, 1.0, v54
	v_add_f32_e32 v55, 1.0, v55
	v_rcp_f32_e32 v54, v54
	v_rcp_f32_e32 v55, v55
	s_nop 0
	v_pk_mul_f32 v[54:55], v[56:57], v[54:55]
	s_nop 0
	v_pk_mul_f32 v[52:53], v[52:53], v[54:55]
	s_nop 0
	v_cvt_pk_bf16_f32 v51, v52, v53
	v_mul_f32_e32 v52, 0xbfb8aa3b, v46
	v_mul_f32_e32 v53, 0xbfb8aa3b, v47
	v_exp_f32_e32 v52, v52
	v_exp_f32_e32 v53, v53
	global_store_dwordx2 v[66:67], v[50:51], off offset:32
	v_add_u32_e32 v50, 0x90, v143
	v_add_f32_e32 v52, 1.0, v52
	v_add_f32_e32 v53, 1.0, v53
	v_rcp_f32_e32 v52, v52
	v_rcp_f32_e32 v53, v53
	v_mad_i64_i32 v[50:51], s[4:5], v50, s6, v[138:139]
	v_lshl_add_u64 v[50:51], v[50:51], 0, s[0:1]
	v_pk_mul_f32 v[46:47], v[46:47], v[52:53]
	v_lshl_add_u64 v[50:51], v[50:51], 0, s[8:9]
	v_pk_mul_f32 v[42:43], v[42:43], v[46:47]
	v_mul_f32_e32 v46, 0xbfb8aa3b, v48
	v_mul_f32_e32 v47, 0xbfb8aa3b, v49
	v_exp_f32_e32 v46, v46
	v_exp_f32_e32 v47, v47
	v_lshl_add_u64 v[50:51], v[50:51], 0, v[0:1]
	v_cvt_pk_bf16_f32 v42, v42, v43
	v_add_f32_e32 v46, 1.0, v46
	v_add_f32_e32 v47, 1.0, v47
	v_rcp_f32_e32 v46, v46
	v_rcp_f32_e32 v47, v47
	s_nop 0
	v_pk_mul_f32 v[46:47], v[48:49], v[46:47]
	s_nop 0
	v_pk_mul_f32 v[44:45], v[44:45], v[46:47]
	s_nop 0
	v_cvt_pk_bf16_f32 v43, v44, v45
	global_store_dwordx2 v[50:51], v[42:43], off
	v_mul_f32_e32 v42, 0xbfb8aa3b, v38
	v_mul_f32_e32 v43, 0xbfb8aa3b, v39
	v_exp_f32_e32 v42, v42
	v_exp_f32_e32 v43, v43
	v_add_f32_e32 v42, 1.0, v42
	v_add_f32_e32 v43, 1.0, v43
	v_rcp_f32_e32 v42, v42
	v_rcp_f32_e32 v43, v43
	s_nop 0
	v_pk_mul_f32 v[38:39], v[38:39], v[42:43]
	s_nop 0
	v_pk_mul_f32 v[34:35], v[34:35], v[38:39]
	v_mul_f32_e32 v38, 0xbfb8aa3b, v40
	v_mul_f32_e32 v39, 0xbfb8aa3b, v41
	v_exp_f32_e32 v38, v38
	v_exp_f32_e32 v39, v39
	v_cvt_pk_bf16_f32 v34, v34, v35
	v_add_f32_e32 v38, 1.0, v38
	v_add_f32_e32 v39, 1.0, v39
	v_rcp_f32_e32 v38, v38
	v_rcp_f32_e32 v39, v39
	s_nop 0
	v_pk_mul_f32 v[38:39], v[40:41], v[38:39]
	s_nop 0
	v_pk_mul_f32 v[36:37], v[36:37], v[38:39]
	s_nop 0
	v_cvt_pk_bf16_f32 v35, v36, v37
	v_mul_f32_e32 v36, 0xbfb8aa3b, v30
	v_mul_f32_e32 v37, 0xbfb8aa3b, v31
	v_exp_f32_e32 v36, v36
	v_exp_f32_e32 v37, v37
	global_store_dwordx2 v[50:51], v[34:35], off offset:32
	v_add_u32_e32 v34, 0xa0, v143
	v_add_f32_e32 v36, 1.0, v36
	v_add_f32_e32 v37, 1.0, v37
	v_rcp_f32_e32 v36, v36
	v_rcp_f32_e32 v37, v37
	v_mad_i64_i32 v[34:35], s[4:5], v34, s6, v[138:139]
	v_lshl_add_u64 v[34:35], v[34:35], 0, s[0:1]
	v_pk_mul_f32 v[30:31], v[30:31], v[36:37]
	v_lshl_add_u64 v[34:35], v[34:35], 0, s[8:9]
	v_pk_mul_f32 v[26:27], v[26:27], v[30:31]
	v_mul_f32_e32 v30, 0xbfb8aa3b, v32
	v_mul_f32_e32 v31, 0xbfb8aa3b, v33
	v_exp_f32_e32 v30, v30
	v_exp_f32_e32 v31, v31
	v_lshl_add_u64 v[34:35], v[34:35], 0, v[0:1]
	v_cvt_pk_bf16_f32 v26, v26, v27
	v_add_f32_e32 v30, 1.0, v30
	v_add_f32_e32 v31, 1.0, v31
	v_rcp_f32_e32 v30, v30
	v_rcp_f32_e32 v31, v31
	s_nop 0
	v_pk_mul_f32 v[30:31], v[32:33], v[30:31]
	s_nop 0
	v_pk_mul_f32 v[28:29], v[28:29], v[30:31]
	s_nop 0
	v_cvt_pk_bf16_f32 v27, v28, v29
	global_store_dwordx2 v[34:35], v[26:27], off
	v_mul_f32_e32 v26, 0xbfb8aa3b, v22
	v_mul_f32_e32 v27, 0xbfb8aa3b, v23
	v_exp_f32_e32 v26, v26
	v_exp_f32_e32 v27, v27
	v_add_f32_e32 v26, 1.0, v26
	v_add_f32_e32 v27, 1.0, v27
	v_rcp_f32_e32 v26, v26
	v_rcp_f32_e32 v27, v27
	s_nop 0
	v_pk_mul_f32 v[22:23], v[22:23], v[26:27]
	s_nop 0
	v_pk_mul_f32 v[18:19], v[18:19], v[22:23]
	v_mul_f32_e32 v22, 0xbfb8aa3b, v24
	v_mul_f32_e32 v23, 0xbfb8aa3b, v25
	v_exp_f32_e32 v22, v22
	v_exp_f32_e32 v23, v23
	v_cvt_pk_bf16_f32 v18, v18, v19
	v_add_f32_e32 v22, 1.0, v22
	v_add_f32_e32 v23, 1.0, v23
	v_rcp_f32_e32 v22, v22
	v_rcp_f32_e32 v23, v23
	s_nop 0
	v_pk_mul_f32 v[22:23], v[24:25], v[22:23]
	s_nop 0
	v_pk_mul_f32 v[20:21], v[20:21], v[22:23]
	s_nop 0
	v_cvt_pk_bf16_f32 v19, v20, v21
	v_mul_f32_e32 v20, 0xbfb8aa3b, v14
	v_mul_f32_e32 v21, 0xbfb8aa3b, v15
	v_exp_f32_e32 v20, v20
	v_exp_f32_e32 v21, v21
	global_store_dwordx2 v[34:35], v[18:19], off offset:32
	v_add_u32_e32 v18, 0xb0, v143
	v_add_f32_e32 v20, 1.0, v20
	v_add_f32_e32 v21, 1.0, v21
	v_rcp_f32_e32 v20, v20
	v_rcp_f32_e32 v21, v21
	v_mad_i64_i32 v[18:19], s[4:5], v18, s6, v[138:139]
	v_lshl_add_u64 v[18:19], v[18:19], 0, s[0:1]
	v_pk_mul_f32 v[14:15], v[14:15], v[20:21]
	v_lshl_add_u64 v[18:19], v[18:19], 0, s[8:9]
	v_pk_mul_f32 v[10:11], v[10:11], v[14:15]
	v_mul_f32_e32 v14, 0xbfb8aa3b, v16
	v_mul_f32_e32 v15, 0xbfb8aa3b, v17
	v_exp_f32_e32 v14, v14
	v_exp_f32_e32 v15, v15
	v_lshl_add_u64 v[18:19], v[18:19], 0, v[0:1]
	v_cvt_pk_bf16_f32 v10, v10, v11
	v_add_f32_e32 v14, 1.0, v14
	v_add_f32_e32 v15, 1.0, v15
	v_rcp_f32_e32 v14, v14
	v_rcp_f32_e32 v15, v15
	s_mov_b64 s[0:1], -1
	v_pk_mul_f32 v[14:15], v[16:17], v[14:15]
	s_nop 0
	v_pk_mul_f32 v[12:13], v[12:13], v[14:15]
	s_nop 0
	v_cvt_pk_bf16_f32 v11, v12, v13
	global_store_dwordx2 v[18:19], v[10:11], off
	v_mul_f32_e32 v10, 0xbfb8aa3b, v6
	v_mul_f32_e32 v11, 0xbfb8aa3b, v7
	v_exp_f32_e32 v10, v10
	v_exp_f32_e32 v11, v11
	v_add_f32_e32 v10, 1.0, v10
	v_add_f32_e32 v11, 1.0, v11
	v_rcp_f32_e32 v10, v10
	v_rcp_f32_e32 v11, v11
	s_nop 0
	v_pk_mul_f32 v[6:7], v[6:7], v[10:11]
	s_nop 0
	v_pk_mul_f32 v[2:3], v[2:3], v[6:7]
	v_mul_f32_e32 v6, 0xbfb8aa3b, v8
	v_mul_f32_e32 v7, 0xbfb8aa3b, v9
	v_exp_f32_e32 v6, v6
	v_exp_f32_e32 v7, v7
	v_cvt_pk_bf16_f32 v2, v2, v3
	v_add_f32_e32 v6, 1.0, v6
	v_add_f32_e32 v7, 1.0, v7
	v_rcp_f32_e32 v6, v6
	v_rcp_f32_e32 v7, v7
	s_nop 0
	v_pk_mul_f32 v[6:7], v[8:9], v[6:7]
	s_nop 0
	v_pk_mul_f32 v[4:5], v[4:5], v[6:7]
	s_nop 0
	v_cvt_pk_bf16_f32 v3, v4, v5
	global_store_dwordx2 v[18:19], v[2:3], off offset:32
	s_cbranch_vccnz .LBB0_912
	s_andn2_b64 vcc, exec, s[36:37]
	s_cbranch_vccnz .LBB0_911
	s_barrier
	s_branch .LBB0_911

.LBB0_943:
	v_writelane_b32 v255, s0, 40
	v_writelane_b32 v255, s1, 41
	v_writelane_b32 v255, s2, 42
	v_writelane_b32 v255, s3, 43
	v_writelane_b32 v255, s4, 44
	v_readlane_b32 s2, v254, 44
	v_readlane_b32 s3, v255, 62
	s_nop 3
	s_cmp_eq_u32 s2, s3
	s_cbranch_scc1 .Lacq_done_b
	s_cmp_eq_u32 s2, 9
	s_cbranch_scc0 .Lacq_done_b
	v_readlane_b32 s0, v254, 10
	v_readlane_b32 s1, v254, 11
	s_nop 3
	s_add_u32 s0, s0, 0x16900
	s_addc_u32 s1, s1, 0
	s_mov_b32 s3, 0

.Lacq_done_b:
	v_readlane_b32 s0, v255, 40
	v_readlane_b32 s1, v255, 41
	v_readlane_b32 s2, v255, 42
	v_readlane_b32 s3, v255, 43
	v_readlane_b32 s4, v255, 44
	s_nop 3
	s_lshl_b32 s1, s66, 2
	s_or_b32 s27, s1, s21
	s_cmp_gt_i32 s27, 19
	s_cselect_b64 s[4:5], -1, 0
	s_cmp_gt_u32 s1, 27
	s_cselect_b64 s[12:13], -1, 0
	s_cmp_gt_u32 s27, 29
	s_cselect_b64 s[88:89], -1, 0
	s_cmp_gt_u32 s1, 35
	s_cselect_b64 s[56:57], -1, 0
	s_cmp_gt_u32 s27, 41
	s_cselect_b64 s[54:55], -1, 0
	s_lshl_b32 s2, s27, 6
	v_readlane_b32 s34, v253, 49
	s_add_i32 s34, s2, 0xfffff580
	s_cmp_lt_u32 s27, 26
	s_cselect_b64 s[42:43], -1, 0
	s_and_b64 s[6:7], s[42:43], exec
	s_movk_i32 s1, 0xffec
	s_cselect_b32 s1, s1, 0xffffffe6
	s_add_i32 s1, s1, s27
	s_and_b64 s[6:7], s[42:43], exec
	s_cselect_b32 s27, 0, 0x180
	s_lshl_b32 s76, s1, 6
	s_ashr_i32 s77, s76, 31
	s_add_i32 s1, s66, -1
	s_cmp_gt_u32 s1, 1
	s_cselect_b64 s[46:47], -1, 0
	s_cmp_lg_u32 s66, 3
	s_cselect_b64 s[70:71], -1, 0
	s_cmp_eq_u32 s66, 1
	v_mov_b32_e32 v0, 0x3e38aa3b
	s_cselect_b64 s[68:69], -1, 0
	s_lshl_b32 s28, s0, 8
	v_readlane_b32 s35, v253, 50
	v_cndmask_b32_e64 v154, 1.0, v0, s[42:43]
	s_add_i32 s28, s28, s22
	s_mov_b32 s3, s35
	v_mov_b32_e32 v155, v154
	v_or_b32_e32 v156, s28, v139
	s_mov_b64 s[0:1], -1
	s_and_b64 vcc, exec, s[4:5]
	s_cbranch_vccz .LBB0_968
	s_and_b64 vcc, exec, s[12:13]
	s_cbranch_vccz .LBB0_958
	v_readlane_b32 s0, v254, 35
	v_readlane_b32 s1, v254, 36
	s_mov_b64 s[6:7], -1
	s_and_b64 vcc, exec, s[88:89]
	v_mov_b64_e32 v[130:131], s[0:1]
	v_mad_i64_i32 v[130:131], s[0:1], v156, s52, v[130:131]
	s_cbranch_vccz .LBB0_955
	s_mov_b64 s[0:1], -1
	s_and_b64 vcc, exec, s[56:57]
	s_cbranch_vccz .LBB0_952
	s_and_b64 vcc, exec, s[54:55]
	s_cbranch_vccz .LBB0_949
	v_lshl_add_u64 v[132:133], s[34:35], 1, v[130:131]
	s_mov_b64 s[0:1], 0xb00
	v_lshl_add_u64 v[132:133], v[132:133], 0, s[0:1]
	s_mov_b64 s[0:1], 0

.LBB0_1378:
	s_add_i32 s54, s54, 1
	s_cmp_eq_u32 s54, 15
	s_cselect_b32 s54, s55, s54
	v_readlane_b32 s26, v254, 21
	v_readlane_b32 s36, v254, 25
	v_readlane_b32 s40, v254, 29
	s_cmp_ge_i32 s54, s55
	v_readlane_b32 s27, v254, 22
	v_readlane_b32 s37, v254, 26
	v_readlane_b32 s41, v254, 30
	s_cbranch_scc1 .Lskip_seam
	s_cmp_eq_u32 s54, 6
	s_cbranch_scc1 .Lskip_seam
	s_cmp_eq_u32 s54, 9
	s_cbranch_scc0 .LBB0_1379
.Lskip_seam:
	s_getpc_b64 s[98:99]
